# PROJ_EVEN tile columns 9/10: left half as 8 dwordx4 stores, right half V^T via DPP quad transposes (16 dwordx2 instead of 64 short stores)
# baseline (speedup 1.0000x reference)
; DI bf16_t f2bf(float x) { unsigned u = __float_as_uint(x); u += 0x7fffu + ((u >> 16) & 1u); return (bf16_t)(u >> 16); }
; DI unsigned pack2(float a, float b) { f32x2 v = {a, b}; return __builtin_bit_cast(unsigned, __builtin_convertvector(v, hwbf16x2)); }
; template <int EPI>
; DI void gemm8_epilogue(const GemmArgs& g, f32x4 (&acc)[2][2][4][2], const int brow, const int bcol, const int wr, const int wc, const int fr, const int fq) {
;     ...
;         if ((bcol == 2304 || bcol == 2560) && bj == 1) {
;           bf16_t* VT = (bf16_t*)(bcol == 2304 ? g.out1 : g.out2);
; #pragma unroll
;           for (int m = 0; m < 4; ++m) {
;             const int row = r0 + m * 16, b = row >> 12, t = row & 4095;
; #pragma unroll
;             for (int n = 0; n < 2; ++n)
; #pragma unroll
;               for (int j = 0; j < 4; ++j) {
;                 const int d = wc * 32 + n * 16 + fq * 4 + j;
;                 VT[((size_t)((b * 2 + (d >> 6)) * 64 + (d & 63))) * SEQ + t] = f2bf(acc[ai][bj][m][n][j]);
;               }
;           }
;         } else {
;           bf16_t* P = (bf16_t*)g.out0;
; #pragma unroll
;           for (int n = 0; n < 2; ++n) {
;             const int col = cb + n * 16 + fq * 4;
;             if (col < 2840) {
; #pragma unroll
;               for (int m = 0; m < 4; ++m) {
;                 u32x2 o; o.x = pack2(acc[ai][bj][m][n][0], acc[ai][bj][m][n][1]); o.y = pack2(acc[ai][bj][m][n][2], acc[ai][bj][m][n][3]);
;                 *(u32x2*)&P[(size_t)(r0 + m * 16) * LDP_E + col] = o;
;               }
;             }
;           }
.Lpe_orig:
	s_cmp_lt_i32 s22, 11
	s_cbranch_scc0 .Lpe_orig2
	v_and_b32_e32 v150, 12, v144
	v_add_u32_e32 v150, v138, v150
	v_mov_b32_e32 v151, 0
	v_lshl_add_u64 v[150:151], v[150:151], 1, s[60:61]
	s_mov_b64 s[40:41], 0x17000
	s_mov_b64 s[50:51], 0x73000
	v_mad_i64_i32 v[152:153], vcc, v145, s95, v[150:151]
	v_cvt_pk_bf16_f32 v126, v126, v127
	v_cvt_pk_bf16_f32 v127, v128, v129
	v_cvt_pk_bf16_f32 v128, v114, v115
	v_cvt_pk_bf16_f32 v129, v116, v117
	s_nop 1
	v_permlane32_swap_b32_e32 v126, v128
	v_permlane32_swap_b32_e32 v127, v129
	s_nop 1
	v_permlane16_swap_b32_e32 v126, v128
	v_permlane16_swap_b32_e32 v127, v129
	global_store_dwordx4 v[152:153], v[126:129], off
	v_lshl_add_u64 v[152:153], v[152:153], 0, s[40:41]
	v_cvt_pk_bf16_f32 v122, v122, v123
	v_cvt_pk_bf16_f32 v123, v124, v125
	v_cvt_pk_bf16_f32 v124, v106, v107
	v_cvt_pk_bf16_f32 v125, v108, v109
	s_nop 1
	v_permlane32_swap_b32_e32 v122, v124
	v_permlane32_swap_b32_e32 v123, v125
	s_nop 1
	v_permlane16_swap_b32_e32 v122, v124
	v_permlane16_swap_b32_e32 v123, v125
	global_store_dwordx4 v[152:153], v[122:125], off
	v_lshl_add_u64 v[152:153], v[152:153], 0, s[40:41]
	v_cvt_pk_bf16_f32 v118, v118, v119
	v_cvt_pk_bf16_f32 v119, v120, v121
	v_cvt_pk_bf16_f32 v120, v102, v103
	v_cvt_pk_bf16_f32 v121, v104, v105
	s_nop 1
	v_permlane32_swap_b32_e32 v118, v120
	v_permlane32_swap_b32_e32 v119, v121
	s_nop 1
	v_permlane16_swap_b32_e32 v118, v120
	v_permlane16_swap_b32_e32 v119, v121
	global_store_dwordx4 v[152:153], v[118:121], off
	v_lshl_add_u64 v[152:153], v[152:153], 0, s[40:41]
	v_cvt_pk_bf16_f32 v110, v110, v111
	v_cvt_pk_bf16_f32 v111, v112, v113
	v_cvt_pk_bf16_f32 v112, v98, v99
	v_cvt_pk_bf16_f32 v113, v100, v101
	s_nop 1
	v_permlane32_swap_b32_e32 v110, v112
	v_permlane32_swap_b32_e32 v111, v113
	s_nop 1
	v_permlane16_swap_b32_e32 v110, v112
	v_permlane16_swap_b32_e32 v111, v113
	global_store_dwordx4 v[152:153], v[110:113], off
	v_lshl_add_u64 v[152:153], v[152:153], 0, s[50:51]
	v_cvt_pk_bf16_f32 v62, v62, v63
	v_cvt_pk_bf16_f32 v63, v64, v65
	v_cvt_pk_bf16_f32 v64, v50, v51
	v_cvt_pk_bf16_f32 v65, v52, v53
	s_nop 1
	v_permlane32_swap_b32_e32 v62, v64
	v_permlane32_swap_b32_e32 v63, v65
	s_nop 1
	v_permlane16_swap_b32_e32 v62, v64
	v_permlane16_swap_b32_e32 v63, v65
	global_store_dwordx4 v[152:153], v[62:65], off
	v_lshl_add_u64 v[152:153], v[152:153], 0, s[40:41]
	v_cvt_pk_bf16_f32 v58, v58, v59
	v_cvt_pk_bf16_f32 v59, v60, v61
	v_cvt_pk_bf16_f32 v60, v42, v43
	v_cvt_pk_bf16_f32 v61, v44, v45
	s_nop 1
	v_permlane32_swap_b32_e32 v58, v60
	v_permlane32_swap_b32_e32 v59, v61
	s_nop 1
	v_permlane16_swap_b32_e32 v58, v60
	v_permlane16_swap_b32_e32 v59, v61
	global_store_dwordx4 v[152:153], v[58:61], off
	v_lshl_add_u64 v[152:153], v[152:153], 0, s[40:41]
	v_cvt_pk_bf16_f32 v54, v54, v55
	v_cvt_pk_bf16_f32 v55, v56, v57
	v_cvt_pk_bf16_f32 v56, v38, v39
	v_cvt_pk_bf16_f32 v57, v40, v41
	s_nop 1
	v_permlane32_swap_b32_e32 v54, v56
	v_permlane32_swap_b32_e32 v55, v57
	s_nop 1
	v_permlane16_swap_b32_e32 v54, v56
	v_permlane16_swap_b32_e32 v55, v57
	global_store_dwordx4 v[152:153], v[54:57], off
	v_lshl_add_u64 v[152:153], v[152:153], 0, s[40:41]
	v_cvt_pk_bf16_f32 v46, v46, v47
	v_cvt_pk_bf16_f32 v47, v48, v49
	v_cvt_pk_bf16_f32 v48, v34, v35
	v_cvt_pk_bf16_f32 v49, v36, v37
	s_nop 1
	v_permlane32_swap_b32_e32 v46, v48
	v_permlane32_swap_b32_e32 v47, v49
	s_nop 1
	v_permlane16_swap_b32_e32 v46, v48
	v_permlane16_swap_b32_e32 v47, v49
	global_store_dwordx4 v[152:153], v[46:49], off
	s_cmp_eq_u32 s22, 9
	v_readlane_b32 s86, v254, 19
	v_readlane_b32 s87, v252, 26
	v_and_b32_e32 v154, 2, v140
	v_cmp_ne_u32_e64 s[38:39], 0, v154
	v_and_b32_e32 v154, 1, v140
	v_cmp_ne_u32_e64 s[40:41], 0, v154
	s_cselect_b32 s25, s79, s86
	s_cselect_b32 s24, s56, s87
	v_and_b32_e32 v150, 3, v140
	v_lshrrev_b32_e32 v151, 2, v140
	v_lshlrev_b32_e32 v150, 5, v150
	v_lshl_add_u32 v150, v151, 3, v150
	s_and_b32 s86, s23, 0xfff
	s_lshl_b32 s86, s86, 1
	v_add_u32_e32 v150, s86, v150
	v_mov_b32_e32 v151, 0
	s_lshr_b32 s86, s23, 12
	s_lshl_b32 s86, s86, 7
	v_add_u32_e32 v152, s86, v144
	v_mov_b32_e32 v153, 0
	v_lshlrev_b64 v[152:153], 13, v[152:153]
	v_lshl_add_u64 v[150:151], s[24:25], 0, v[150:151]
	v_lshl_add_u64 v[152:153], v[150:151], 0, v[152:153]
	s_mov_b64 s[50:51], 0x2000
	s_mov_b64 s[86:87], 0x1a000
	v_cndmask_b32_e64 v154, v78, v94, s[38:39]
	v_cndmask_b32_e64 v155, v70, v86, s[38:39]
	v_cndmask_b32_e64 v156, v14, v30, s[38:39]
	v_cndmask_b32_e64 v157, v6, v22, s[38:39]
	v_mov_b32_dpp v154, v154 quad_perm:[2,3,0,1] row_mask:0xf bank_mask:0xf
	v_mov_b32_dpp v155, v155 quad_perm:[2,3,0,1] row_mask:0xf bank_mask:0xf
	v_mov_b32_dpp v156, v156 quad_perm:[2,3,0,1] row_mask:0xf bank_mask:0xf
	v_mov_b32_dpp v157, v157 quad_perm:[2,3,0,1] row_mask:0xf bank_mask:0xf
	v_cndmask_b32_e64 v94, v94, v154, s[38:39]
	v_cndmask_b32_e64 v78, v154, v78, s[38:39]
	v_cndmask_b32_e64 v86, v86, v155, s[38:39]
	v_cndmask_b32_e64 v70, v155, v70, s[38:39]
	v_cndmask_b32_e64 v30, v30, v156, s[38:39]
	v_cndmask_b32_e64 v14, v156, v14, s[38:39]
	v_cndmask_b32_e64 v22, v22, v157, s[38:39]
	v_cndmask_b32_e64 v6, v157, v6, s[38:39]
	v_cndmask_b32_e64 v154, v86, v94, s[40:41]
	v_cndmask_b32_e64 v155, v70, v78, s[40:41]
	v_cndmask_b32_e64 v156, v22, v30, s[40:41]
	v_cndmask_b32_e64 v157, v6, v14, s[40:41]
	v_mov_b32_dpp v154, v154 quad_perm:[1,0,3,2] row_mask:0xf bank_mask:0xf
	v_mov_b32_dpp v155, v155 quad_perm:[1,0,3,2] row_mask:0xf bank_mask:0xf
	v_mov_b32_dpp v156, v156 quad_perm:[1,0,3,2] row_mask:0xf bank_mask:0xf
	v_mov_b32_dpp v157, v157 quad_perm:[1,0,3,2] row_mask:0xf bank_mask:0xf
	v_cndmask_b32_e64 v94, v94, v154, s[40:41]
; DI bf16_t f2bf(float x) { unsigned u = __float_as_uint(x); u += 0x7fffu + ((u >> 16) & 1u); return (bf16_t)(u >> 16); }
; template <int EPI>
; DI void gemm8_epilogue(const GemmArgs& g, f32x4 (&acc)[2][2][4][2], const int brow, const int bcol, const int wr, const int wc, const int fr, const int fq) {
;     ...
;         if ((bcol == 2304 || bcol == 2560) && bj == 1) {
;           bf16_t* VT = (bf16_t*)(bcol == 2304 ? g.out1 : g.out2);
; #pragma unroll
;           for (int m = 0; m < 4; ++m) {
;             const int row = r0 + m * 16, b = row >> 12, t = row & 4095;
; #pragma unroll
;             for (int n = 0; n < 2; ++n)
; #pragma unroll
;               for (int j = 0; j < 4; ++j) {
;                 const int d = wc * 32 + n * 16 + fq * 4 + j;
;                 VT[((size_t)((b * 2 + (d >> 6)) * 64 + (d & 63))) * SEQ + t] = f2bf(acc[ai][bj][m][n][j]);
;               }
;           }
	v_cndmask_b32_e64 v86, v154, v86, s[40:41]
	v_cndmask_b32_e64 v78, v78, v155, s[40:41]
	v_cndmask_b32_e64 v70, v155, v70, s[40:41]
	v_cndmask_b32_e64 v30, v30, v156, s[40:41]
	v_cndmask_b32_e64 v22, v156, v22, s[40:41]
	v_cndmask_b32_e64 v14, v14, v157, s[40:41]
	v_cndmask_b32_e64 v6, v157, v6, s[40:41]
	v_cvt_pk_bf16_f32 v158, v94, v86
	v_cvt_pk_bf16_f32 v159, v78, v70
	v_cvt_pk_bf16_f32 v160, v30, v22
	v_cvt_pk_bf16_f32 v161, v14, v6
	global_store_dwordx2 v[152:153], v[158:159], off
	global_store_dwordx2 v[152:153], v[160:161], off offset:256
	v_lshl_add_u64 v[152:153], v[152:153], 0, s[50:51]
	v_cndmask_b32_e64 v154, v79, v95, s[38:39]
	v_cndmask_b32_e64 v155, v71, v87, s[38:39]
	v_cndmask_b32_e64 v156, v15, v31, s[38:39]
	v_cndmask_b32_e64 v157, v7, v23, s[38:39]
	v_mov_b32_dpp v154, v154 quad_perm:[2,3,0,1] row_mask:0xf bank_mask:0xf
	v_mov_b32_dpp v155, v155 quad_perm:[2,3,0,1] row_mask:0xf bank_mask:0xf
	v_mov_b32_dpp v156, v156 quad_perm:[2,3,0,1] row_mask:0xf bank_mask:0xf
	v_mov_b32_dpp v157, v157 quad_perm:[2,3,0,1] row_mask:0xf bank_mask:0xf
	v_cndmask_b32_e64 v95, v95, v154, s[38:39]
	v_cndmask_b32_e64 v79, v154, v79, s[38:39]
	v_cndmask_b32_e64 v87, v87, v155, s[38:39]
	v_cndmask_b32_e64 v71, v155, v71, s[38:39]
	v_cndmask_b32_e64 v31, v31, v156, s[38:39]
	v_cndmask_b32_e64 v15, v156, v15, s[38:39]
	v_cndmask_b32_e64 v23, v23, v157, s[38:39]
	v_cndmask_b32_e64 v7, v157, v7, s[38:39]
	v_cndmask_b32_e64 v154, v87, v95, s[40:41]
	v_cndmask_b32_e64 v155, v71, v79, s[40:41]
	v_cndmask_b32_e64 v156, v23, v31, s[40:41]
	v_cndmask_b32_e64 v157, v7, v15, s[40:41]
	v_mov_b32_dpp v154, v154 quad_perm:[1,0,3,2] row_mask:0xf bank_mask:0xf
	v_mov_b32_dpp v155, v155 quad_perm:[1,0,3,2] row_mask:0xf bank_mask:0xf
	v_mov_b32_dpp v156, v156 quad_perm:[1,0,3,2] row_mask:0xf bank_mask:0xf
	v_mov_b32_dpp v157, v157 quad_perm:[1,0,3,2] row_mask:0xf bank_mask:0xf
	v_cndmask_b32_e64 v95, v95, v154, s[40:41]
	v_cndmask_b32_e64 v87, v154, v87, s[40:41]
	v_cndmask_b32_e64 v79, v79, v155, s[40:41]
	v_cndmask_b32_e64 v71, v155, v71, s[40:41]
	v_cndmask_b32_e64 v31, v31, v156, s[40:41]
	v_cndmask_b32_e64 v23, v156, v23, s[40:41]
	v_cndmask_b32_e64 v15, v15, v157, s[40:41]
	v_cndmask_b32_e64 v7, v157, v7, s[40:41]
	v_cvt_pk_bf16_f32 v158, v95, v87
	v_cvt_pk_bf16_f32 v159, v79, v71
	v_cvt_pk_bf16_f32 v160, v31, v23
	v_cvt_pk_bf16_f32 v161, v15, v7
	global_store_dwordx2 v[152:153], v[158:159], off
	global_store_dwordx2 v[152:153], v[160:161], off offset:256
	v_lshl_add_u64 v[152:153], v[152:153], 0, s[50:51]
	v_cndmask_b32_e64 v154, v80, v96, s[38:39]
	v_cndmask_b32_e64 v155, v72, v88, s[38:39]
	v_cndmask_b32_e64 v156, v16, v32, s[38:39]
	v_cndmask_b32_e64 v157, v8, v24, s[38:39]
	v_mov_b32_dpp v154, v154 quad_perm:[2,3,0,1] row_mask:0xf bank_mask:0xf
	v_mov_b32_dpp v155, v155 quad_perm:[2,3,0,1] row_mask:0xf bank_mask:0xf
	v_mov_b32_dpp v156, v156 quad_perm:[2,3,0,1] row_mask:0xf bank_mask:0xf
	v_mov_b32_dpp v157, v157 quad_perm:[2,3,0,1] row_mask:0xf bank_mask:0xf
	v_cndmask_b32_e64 v96, v96, v154, s[38:39]
	v_cndmask_b32_e64 v80, v154, v80, s[38:39]
	v_cndmask_b32_e64 v88, v88, v155, s[38:39]
	v_cndmask_b32_e64 v72, v155, v72, s[38:39]
	v_cndmask_b32_e64 v32, v32, v156, s[38:39]
	v_cndmask_b32_e64 v16, v156, v16, s[38:39]
	v_cndmask_b32_e64 v24, v24, v157, s[38:39]
	v_cndmask_b32_e64 v8, v157, v8, s[38:39]
	v_cndmask_b32_e64 v154, v88, v96, s[40:41]
	v_cndmask_b32_e64 v155, v72, v80, s[40:41]
	v_cndmask_b32_e64 v156, v24, v32, s[40:41]
	v_cndmask_b32_e64 v157, v8, v16, s[40:41]
	v_mov_b32_dpp v154, v154 quad_perm:[1,0,3,2] row_mask:0xf bank_mask:0xf
	v_mov_b32_dpp v155, v155 quad_perm:[1,0,3,2] row_mask:0xf bank_mask:0xf
	v_mov_b32_dpp v156, v156 quad_perm:[1,0,3,2] row_mask:0xf bank_mask:0xf
	v_mov_b32_dpp v157, v157 quad_perm:[1,0,3,2] row_mask:0xf bank_mask:0xf
	v_cndmask_b32_e64 v96, v96, v154, s[40:41]
	v_cndmask_b32_e64 v88, v154, v88, s[40:41]
	v_cndmask_b32_e64 v80, v80, v155, s[40:41]
	v_cndmask_b32_e64 v72, v155, v72, s[40:41]
	v_cndmask_b32_e64 v32, v32, v156, s[40:41]
	v_cndmask_b32_e64 v24, v156, v24, s[40:41]
	v_cndmask_b32_e64 v16, v16, v157, s[40:41]
	v_cndmask_b32_e64 v8, v157, v8, s[40:41]
	v_cvt_pk_bf16_f32 v158, v96, v88
	v_cvt_pk_bf16_f32 v159, v80, v72
	v_cvt_pk_bf16_f32 v160, v32, v24
	v_cvt_pk_bf16_f32 v161, v16, v8
	global_store_dwordx2 v[152:153], v[158:159], off
	global_store_dwordx2 v[152:153], v[160:161], off offset:256
	v_lshl_add_u64 v[152:153], v[152:153], 0, s[50:51]
	v_cndmask_b32_e64 v154, v81, v97, s[38:39]
	v_cndmask_b32_e64 v155, v73, v89, s[38:39]
	v_cndmask_b32_e64 v156, v17, v33, s[38:39]
	v_cndmask_b32_e64 v157, v9, v25, s[38:39]
	v_mov_b32_dpp v154, v154 quad_perm:[2,3,0,1] row_mask:0xf bank_mask:0xf
	v_mov_b32_dpp v155, v155 quad_perm:[2,3,0,1] row_mask:0xf bank_mask:0xf
	v_mov_b32_dpp v156, v156 quad_perm:[2,3,0,1] row_mask:0xf bank_mask:0xf
	v_mov_b32_dpp v157, v157 quad_perm:[2,3,0,1] row_mask:0xf bank_mask:0xf
	v_cndmask_b32_e64 v97, v97, v154, s[38:39]
	v_cndmask_b32_e64 v81, v154, v81, s[38:39]
	v_cndmask_b32_e64 v89, v89, v155, s[38:39]
	v_cndmask_b32_e64 v73, v155, v73, s[38:39]
	v_cndmask_b32_e64 v33, v33, v156, s[38:39]
	v_cndmask_b32_e64 v17, v156, v17, s[38:39]
	v_cndmask_b32_e64 v25, v25, v157, s[38:39]
	v_cndmask_b32_e64 v9, v157, v9, s[38:39]
	v_cndmask_b32_e64 v154, v89, v97, s[40:41]
	v_cndmask_b32_e64 v155, v73, v81, s[40:41]
	v_cndmask_b32_e64 v156, v25, v33, s[40:41]
	v_cndmask_b32_e64 v157, v9, v17, s[40:41]
	v_mov_b32_dpp v154, v154 quad_perm:[1,0,3,2] row_mask:0xf bank_mask:0xf
	v_mov_b32_dpp v155, v155 quad_perm:[1,0,3,2] row_mask:0xf bank_mask:0xf
; DI bf16_t f2bf(float x) { unsigned u = __float_as_uint(x); u += 0x7fffu + ((u >> 16) & 1u); return (bf16_t)(u >> 16); }
; template <int EPI>
; DI void gemm8_epilogue(const GemmArgs& g, f32x4 (&acc)[2][2][4][2], const int brow, const int bcol, const int wr, const int wc, const int fr, const int fq) {
;     ...
;         if ((bcol == 2304 || bcol == 2560) && bj == 1) {
;           bf16_t* VT = (bf16_t*)(bcol == 2304 ? g.out1 : g.out2);
; #pragma unroll
;           for (int m = 0; m < 4; ++m) {
;             const int row = r0 + m * 16, b = row >> 12, t = row & 4095;
; #pragma unroll
;             for (int n = 0; n < 2; ++n)
; #pragma unroll
;               for (int j = 0; j < 4; ++j) {
;                 const int d = wc * 32 + n * 16 + fq * 4 + j;
;                 VT[((size_t)((b * 2 + (d >> 6)) * 64 + (d & 63))) * SEQ + t] = f2bf(acc[ai][bj][m][n][j]);
;               }
;           }
	v_mov_b32_dpp v156, v156 quad_perm:[1,0,3,2] row_mask:0xf bank_mask:0xf
	v_mov_b32_dpp v157, v157 quad_perm:[1,0,3,2] row_mask:0xf bank_mask:0xf
	v_cndmask_b32_e64 v97, v97, v154, s[40:41]
	v_cndmask_b32_e64 v89, v154, v89, s[40:41]
	v_cndmask_b32_e64 v81, v81, v155, s[40:41]
	v_cndmask_b32_e64 v73, v155, v73, s[40:41]
	v_cndmask_b32_e64 v33, v33, v156, s[40:41]
	v_cndmask_b32_e64 v25, v156, v25, s[40:41]
	v_cndmask_b32_e64 v17, v17, v157, s[40:41]
	v_cndmask_b32_e64 v9, v157, v9, s[40:41]
	v_cvt_pk_bf16_f32 v158, v97, v89
	v_cvt_pk_bf16_f32 v159, v81, v73
	v_cvt_pk_bf16_f32 v160, v33, v25
	v_cvt_pk_bf16_f32 v161, v17, v9
	global_store_dwordx2 v[152:153], v[158:159], off
	global_store_dwordx2 v[152:153], v[160:161], off offset:256
	v_lshl_add_u64 v[152:153], v[152:153], 0, s[86:87]
	v_cndmask_b32_e64 v154, v74, v90, s[38:39]
	v_cndmask_b32_e64 v155, v66, v82, s[38:39]
	v_cndmask_b32_e64 v156, v10, v26, s[38:39]
	v_cndmask_b32_e64 v157, v2, v18, s[38:39]
	v_mov_b32_dpp v154, v154 quad_perm:[2,3,0,1] row_mask:0xf bank_mask:0xf
	v_mov_b32_dpp v155, v155 quad_perm:[2,3,0,1] row_mask:0xf bank_mask:0xf
	v_mov_b32_dpp v156, v156 quad_perm:[2,3,0,1] row_mask:0xf bank_mask:0xf
	v_mov_b32_dpp v157, v157 quad_perm:[2,3,0,1] row_mask:0xf bank_mask:0xf
	v_cndmask_b32_e64 v90, v90, v154, s[38:39]
	v_cndmask_b32_e64 v74, v154, v74, s[38:39]
	v_cndmask_b32_e64 v82, v82, v155, s[38:39]
	v_cndmask_b32_e64 v66, v155, v66, s[38:39]
	v_cndmask_b32_e64 v26, v26, v156, s[38:39]
	v_cndmask_b32_e64 v10, v156, v10, s[38:39]
	v_cndmask_b32_e64 v18, v18, v157, s[38:39]
	v_cndmask_b32_e64 v2, v157, v2, s[38:39]
	v_cndmask_b32_e64 v154, v82, v90, s[40:41]
	v_cndmask_b32_e64 v155, v66, v74, s[40:41]
	v_cndmask_b32_e64 v156, v18, v26, s[40:41]
	v_cndmask_b32_e64 v157, v2, v10, s[40:41]
	v_mov_b32_dpp v154, v154 quad_perm:[1,0,3,2] row_mask:0xf bank_mask:0xf
	v_mov_b32_dpp v155, v155 quad_perm:[1,0,3,2] row_mask:0xf bank_mask:0xf
	v_mov_b32_dpp v156, v156 quad_perm:[1,0,3,2] row_mask:0xf bank_mask:0xf
	v_mov_b32_dpp v157, v157 quad_perm:[1,0,3,2] row_mask:0xf bank_mask:0xf
	v_cndmask_b32_e64 v90, v90, v154, s[40:41]
	v_cndmask_b32_e64 v82, v154, v82, s[40:41]
	v_cndmask_b32_e64 v74, v74, v155, s[40:41]
	v_cndmask_b32_e64 v66, v155, v66, s[40:41]
	v_cndmask_b32_e64 v26, v26, v156, s[40:41]
	v_cndmask_b32_e64 v18, v156, v18, s[40:41]
	v_cndmask_b32_e64 v10, v10, v157, s[40:41]
	v_cndmask_b32_e64 v2, v157, v2, s[40:41]
	v_cvt_pk_bf16_f32 v158, v90, v82
	v_cvt_pk_bf16_f32 v159, v74, v66
	v_cvt_pk_bf16_f32 v160, v26, v18
	v_cvt_pk_bf16_f32 v161, v10, v2
	global_store_dwordx2 v[152:153], v[158:159], off
	global_store_dwordx2 v[152:153], v[160:161], off offset:256
	v_lshl_add_u64 v[152:153], v[152:153], 0, s[50:51]
	v_cndmask_b32_e64 v154, v75, v91, s[38:39]
	v_cndmask_b32_e64 v155, v67, v83, s[38:39]
	v_cndmask_b32_e64 v156, v11, v27, s[38:39]
	v_cndmask_b32_e64 v157, v3, v19, s[38:39]
	v_mov_b32_dpp v154, v154 quad_perm:[2,3,0,1] row_mask:0xf bank_mask:0xf
	v_mov_b32_dpp v155, v155 quad_perm:[2,3,0,1] row_mask:0xf bank_mask:0xf
	v_mov_b32_dpp v156, v156 quad_perm:[2,3,0,1] row_mask:0xf bank_mask:0xf
	v_mov_b32_dpp v157, v157 quad_perm:[2,3,0,1] row_mask:0xf bank_mask:0xf
	v_cndmask_b32_e64 v91, v91, v154, s[38:39]
	v_cndmask_b32_e64 v75, v154, v75, s[38:39]
	v_cndmask_b32_e64 v83, v83, v155, s[38:39]
	v_cndmask_b32_e64 v67, v155, v67, s[38:39]
	v_cndmask_b32_e64 v27, v27, v156, s[38:39]
	v_cndmask_b32_e64 v11, v156, v11, s[38:39]
	v_cndmask_b32_e64 v19, v19, v157, s[38:39]
	v_cndmask_b32_e64 v3, v157, v3, s[38:39]
	v_cndmask_b32_e64 v154, v83, v91, s[40:41]
	v_cndmask_b32_e64 v155, v67, v75, s[40:41]
	v_cndmask_b32_e64 v156, v19, v27, s[40:41]
	v_cndmask_b32_e64 v157, v3, v11, s[40:41]
	v_mov_b32_dpp v154, v154 quad_perm:[1,0,3,2] row_mask:0xf bank_mask:0xf
	v_mov_b32_dpp v155, v155 quad_perm:[1,0,3,2] row_mask:0xf bank_mask:0xf
	v_mov_b32_dpp v156, v156 quad_perm:[1,0,3,2] row_mask:0xf bank_mask:0xf
	v_mov_b32_dpp v157, v157 quad_perm:[1,0,3,2] row_mask:0xf bank_mask:0xf
	v_cndmask_b32_e64 v91, v91, v154, s[40:41]
	v_cndmask_b32_e64 v83, v154, v83, s[40:41]
	v_cndmask_b32_e64 v75, v75, v155, s[40:41]
	v_cndmask_b32_e64 v67, v155, v67, s[40:41]
	v_cndmask_b32_e64 v27, v27, v156, s[40:41]
; DI bf16_t f2bf(float x) { unsigned u = __float_as_uint(x); u += 0x7fffu + ((u >> 16) & 1u); return (bf16_t)(u >> 16); }
; template <int EPI>
; DI void gemm8_epilogue(const GemmArgs& g, f32x4 (&acc)[2][2][4][2], const int brow, const int bcol, const int wr, const int wc, const int fr, const int fq) {
;     ...
;         if ((bcol == 2304 || bcol == 2560) && bj == 1) {
;           bf16_t* VT = (bf16_t*)(bcol == 2304 ? g.out1 : g.out2);
; #pragma unroll
;           for (int m = 0; m < 4; ++m) {
;             const int row = r0 + m * 16, b = row >> 12, t = row & 4095;
; #pragma unroll
;             for (int n = 0; n < 2; ++n)
; #pragma unroll
;               for (int j = 0; j < 4; ++j) {
;                 const int d = wc * 32 + n * 16 + fq * 4 + j;
;                 VT[((size_t)((b * 2 + (d >> 6)) * 64 + (d & 63))) * SEQ + t] = f2bf(acc[ai][bj][m][n][j]);
;               }
;           }
	v_cndmask_b32_e64 v19, v156, v19, s[40:41]
	v_cndmask_b32_e64 v11, v11, v157, s[40:41]
	v_cndmask_b32_e64 v3, v157, v3, s[40:41]
	v_cvt_pk_bf16_f32 v158, v91, v83
	v_cvt_pk_bf16_f32 v159, v75, v67
	v_cvt_pk_bf16_f32 v160, v27, v19
	v_cvt_pk_bf16_f32 v161, v11, v3
	global_store_dwordx2 v[152:153], v[158:159], off
	global_store_dwordx2 v[152:153], v[160:161], off offset:256
	v_lshl_add_u64 v[152:153], v[152:153], 0, s[50:51]
	v_cndmask_b32_e64 v154, v76, v92, s[38:39]
	v_cndmask_b32_e64 v155, v68, v84, s[38:39]
	v_cndmask_b32_e64 v156, v12, v28, s[38:39]
	v_cndmask_b32_e64 v157, v4, v20, s[38:39]
	v_mov_b32_dpp v154, v154 quad_perm:[2,3,0,1] row_mask:0xf bank_mask:0xf
	v_mov_b32_dpp v155, v155 quad_perm:[2,3,0,1] row_mask:0xf bank_mask:0xf
	v_mov_b32_dpp v156, v156 quad_perm:[2,3,0,1] row_mask:0xf bank_mask:0xf
	v_mov_b32_dpp v157, v157 quad_perm:[2,3,0,1] row_mask:0xf bank_mask:0xf
	v_cndmask_b32_e64 v92, v92, v154, s[38:39]
	v_cndmask_b32_e64 v76, v154, v76, s[38:39]
	v_cndmask_b32_e64 v84, v84, v155, s[38:39]
	v_cndmask_b32_e64 v68, v155, v68, s[38:39]
	v_cndmask_b32_e64 v28, v28, v156, s[38:39]
	v_cndmask_b32_e64 v12, v156, v12, s[38:39]
	v_cndmask_b32_e64 v20, v20, v157, s[38:39]
	v_cndmask_b32_e64 v4, v157, v4, s[38:39]
	v_cndmask_b32_e64 v154, v84, v92, s[40:41]
	v_cndmask_b32_e64 v155, v68, v76, s[40:41]
	v_cndmask_b32_e64 v156, v20, v28, s[40:41]
	v_cndmask_b32_e64 v157, v4, v12, s[40:41]
	v_mov_b32_dpp v154, v154 quad_perm:[1,0,3,2] row_mask:0xf bank_mask:0xf
	v_mov_b32_dpp v155, v155 quad_perm:[1,0,3,2] row_mask:0xf bank_mask:0xf
	v_mov_b32_dpp v156, v156 quad_perm:[1,0,3,2] row_mask:0xf bank_mask:0xf
	v_mov_b32_dpp v157, v157 quad_perm:[1,0,3,2] row_mask:0xf bank_mask:0xf
	v_cndmask_b32_e64 v92, v92, v154, s[40:41]
	v_cndmask_b32_e64 v84, v154, v84, s[40:41]
	v_cndmask_b32_e64 v76, v76, v155, s[40:41]
	v_cndmask_b32_e64 v68, v155, v68, s[40:41]
	v_cndmask_b32_e64 v28, v28, v156, s[40:41]
	v_cndmask_b32_e64 v20, v156, v20, s[40:41]
	v_cndmask_b32_e64 v12, v12, v157, s[40:41]
	v_cndmask_b32_e64 v4, v157, v4, s[40:41]
	v_cvt_pk_bf16_f32 v158, v92, v84
	v_cvt_pk_bf16_f32 v159, v76, v68
	v_cvt_pk_bf16_f32 v160, v28, v20
	v_cvt_pk_bf16_f32 v161, v12, v4
	global_store_dwordx2 v[152:153], v[158:159], off
	global_store_dwordx2 v[152:153], v[160:161], off offset:256
	v_lshl_add_u64 v[152:153], v[152:153], 0, s[50:51]
	v_cndmask_b32_e64 v154, v77, v93, s[38:39]
	v_cndmask_b32_e64 v155, v69, v85, s[38:39]
	v_cndmask_b32_e64 v156, v13, v29, s[38:39]
	v_cndmask_b32_e64 v157, v5, v21, s[38:39]
	v_mov_b32_dpp v154, v154 quad_perm:[2,3,0,1] row_mask:0xf bank_mask:0xf
	v_mov_b32_dpp v155, v155 quad_perm:[2,3,0,1] row_mask:0xf bank_mask:0xf
	v_mov_b32_dpp v156, v156 quad_perm:[2,3,0,1] row_mask:0xf bank_mask:0xf
	v_mov_b32_dpp v157, v157 quad_perm:[2,3,0,1] row_mask:0xf bank_mask:0xf
	v_cndmask_b32_e64 v93, v93, v154, s[38:39]
	v_cndmask_b32_e64 v77, v154, v77, s[38:39]
	v_cndmask_b32_e64 v85, v85, v155, s[38:39]
	v_cndmask_b32_e64 v69, v155, v69, s[38:39]
	v_cndmask_b32_e64 v29, v29, v156, s[38:39]
	v_cndmask_b32_e64 v13, v156, v13, s[38:39]
	v_cndmask_b32_e64 v21, v21, v157, s[38:39]
	v_cndmask_b32_e64 v5, v157, v5, s[38:39]
	v_cndmask_b32_e64 v154, v85, v93, s[40:41]
	v_cndmask_b32_e64 v155, v69, v77, s[40:41]
	v_cndmask_b32_e64 v156, v21, v29, s[40:41]
	v_cndmask_b32_e64 v157, v5, v13, s[40:41]
	v_mov_b32_dpp v154, v154 quad_perm:[1,0,3,2] row_mask:0xf bank_mask:0xf
	v_mov_b32_dpp v155, v155 quad_perm:[1,0,3,2] row_mask:0xf bank_mask:0xf
	v_mov_b32_dpp v156, v156 quad_perm:[1,0,3,2] row_mask:0xf bank_mask:0xf
	v_mov_b32_dpp v157, v157 quad_perm:[1,0,3,2] row_mask:0xf bank_mask:0xf
	v_cndmask_b32_e64 v93, v93, v154, s[40:41]
	v_cndmask_b32_e64 v85, v154, v85, s[40:41]
	v_cndmask_b32_e64 v77, v77, v155, s[40:41]
	v_cndmask_b32_e64 v69, v155, v69, s[40:41]
	v_cndmask_b32_e64 v29, v29, v156, s[40:41]
	v_cndmask_b32_e64 v21, v156, v21, s[40:41]
	v_cndmask_b32_e64 v13, v13, v157, s[40:41]
	v_cndmask_b32_e64 v5, v157, v5, s[40:41]
	v_cvt_pk_bf16_f32 v158, v93, v85
	v_cvt_pk_bf16_f32 v159, v77, v69
	v_cvt_pk_bf16_f32 v160, v29, v21
	v_cvt_pk_bf16_f32 v161, v13, v5
	global_store_dwordx2 v[152:153], v[158:159], off
	global_store_dwordx2 v[152:153], v[160:161], off offset:256
	s_branch .LBB0_596
